# phase start: rstd-table second segment's ssq lines are touched early (one extra load per thread) so the two serialized load-wait segments overlap; on top of static leading-half priority
# speedup vs baseline: 1.0032x; 1.0032x over previous
.LBB0_65:
	s_or_b64 exec, exec, s[8:9]
	s_bitcmp1_b32 s14, 3
	v_readlane_b32 s2, v255, 29
	s_cselect_b32 s44, s66, s2
	v_and_b32_e32 v3, 0xff, v0
	v_readlane_b32 s2, v255, 13
	v_readlane_b32 s3, v255, 30
	s_cselect_b32 s45, s67, s3
	v_lshl_add_u32 v1, v3, 2, s2
	v_cmp_lt_i32_e32 vcc, -1, v4
	v_lshl_add_u32 v1, v2, 10, v1
	v_mov_b32_e32 v30, s5
	v_mov_b32_e32 v31, s4
	v_mov_b32_e32 v33, 0x100
	v_cmp_gt_u32_e64 s[100:101], v33, v0
	s_nop 1
	v_cndmask_b32_e64 v30, v30, v31, s[100:101]
	v_max_i32_e32 v30, 0, v30
	v_lshl_or_b32 v30, v30, 8, v3
	v_mov_b32_e32 v31, 0
	v_lshlrev_b64 v[30:31], 6, v[30:31]
	v_lshl_add_u64 v[30:31], s[44:45], 0, v[30:31]
	global_load_dword v32, v[30:31], off
	s_and_saveexec_b64 s[6:7], vcc
	s_cbranch_execz .LBB0_67
	v_lshl_or_b32 v140, v4, 8, v3
	v_lshlrev_b64 v[4:5], 6, v[140:141]
	v_lshl_add_u64 v[16:17], s[44:45], 0, v[4:5]
	flat_load_dwordx4 v[4:7], v[16:17]
	flat_load_dwordx4 v[8:11], v[16:17] offset:32
	flat_load_dwordx4 v[12:15], v[16:17] offset:16
	s_nop 0
	flat_load_dwordx4 v[16:19], v[16:17] offset:48
	s_waitcnt vmcnt(0) lgkmcnt(0)
	v_mov_b32_e32 v20, v4
	v_mov_b32_e32 v21, v8
	v_mov_b32_e32 v8, v5
	v_mov_b32_e32 v4, v6
	v_mov_b32_e32 v5, v10
	v_mov_b32_e32 v10, v7
	v_mov_b32_e32 v6, v12
	v_mov_b32_e32 v7, v16
	v_mov_b32_e32 v16, v13
	v_mov_b32_e32 v12, v14
	v_mov_b32_e32 v13, v18
	v_mov_b32_e32 v18, v15
	v_pk_add_f32 v[8:9], v[20:21], v[8:9]
	v_pk_add_f32 v[4:5], v[4:5], v[10:11]
	v_pk_add_f32 v[6:7], v[6:7], v[16:17]
	v_pk_add_f32 v[10:11], v[12:13], v[18:19]
	v_pk_add_f32 v[4:5], v[8:9], v[4:5]
	v_pk_add_f32 v[6:7], v[6:7], v[10:11]
	s_nop 0
	v_pk_add_f32 v[4:5], v[4:5], v[6:7]
	s_nop 0
	v_add_f32_e32 v4, v4, v5
	v_fmamk_f32 v4, v4, 0x3a800000, v250
	v_rsq_f32_e32 v4, v4
	ds_write_b32 v1, v4

.LBB0_79:
	s_or_b64 exec, exec, s[6:7]
	s_waitcnt vmcnt(0)
	s_mov_b32 s4, -1
	s_waitcnt lgkmcnt(0)
	s_barrier
	s_getreg_b32 s5, hwreg(HW_REG_HW_ID, 0, 6)
	s_and_b32 s5, s5, 63
	s_lshl_b32 s5, s5, 2
	s_add_i32 s5, s5, 0
	s_add_i32 s5, s5, 0x20200
	v_mov_b32_e32 v0, s5
	ds_read_b32 v0, v0
	v_mbcnt_lo_u32_b32 v1, s4, 0
	v_mbcnt_hi_u32_b32 v1, s4, v1
	v_readlane_b32 s2, v253, 7
	v_readlane_b32 s3, v253, 8
	s_waitcnt lgkmcnt(0)
	v_readfirstlane_b32 s4, v0
	s_andn2_b64 vcc, exec, s[2:3]
	s_nop 0
	v_lshl_add_u32 v0, s4, 6, v1
	s_nop 0
	v_readfirstlane_b32 s4, v0
	s_cbranch_vccnz .LBB0_131
	v_lshlrev_b32_e32 v4, 4, v0
	v_add_u32_e32 v2, 0x2000, v4
	v_ashrrev_i32_e32 v1, 31, v2
	v_lshrrev_b32_e32 v1, 22, v1
	v_add_u32_e32 v1, v2, v1
	v_ashrrev_i32_e32 v1, 10, v1
	v_mul_i32_i24_e32 v3, 0x400, v1
	v_sub_u32_e32 v2, v2, v3
	v_lshrrev_b32_e32 v3, 4, v2
	v_bitop3_b32 v3, v3, v2, 32 bitop3:0x6c
	v_ashrrev_i32_e32 v2, 31, v3
	v_lshrrev_b32_e32 v2, 26, v2
	v_add_u32_e32 v5, v3, v2
	v_lshlrev_b32_e32 v6, 3, v1
	v_ashrrev_i32_e32 v2, 6, v5
	v_and_b32_e32 v6, -16, v6
	v_add_u32_e32 v6, v2, v6
	v_and_b32_e32 v7, 3, v2
	s_mov_b32 s2, 0x1fffe0
	v_lshrrev_b32_e32 v8, 2, v6
	v_lshlrev_b32_e32 v9, 1, v6
	v_and_b32_e32 v5, 0xc0, v5
	v_and_or_b32 v7, v6, s2, v7
	v_and_b32_e32 v8, 4, v8
	v_and_b32_e32 v9, 24, v9
	v_sub_u32_e32 v3, v3, v5
	v_mov_b32_e32 v12, 1
	v_or3_b32 v7, v7, v8, v9
	v_lshlrev_b32_e32 v8, 5, v1
	v_ashrrev_i16_sdwa v3, v12, sext(v3) dst_sel:DWORD dst_unused:UNUSED_PAD src0_sel:DWORD src1_sel:BYTE_0
	v_and_b32_e32 v8, 32, v8
	v_bfe_i32 v3, v3, 0, 16
	v_add_lshl_u32 v5, v8, v3, 1
	v_lshl_add_u32 v128, v7, 11, v5
	v_lshl_add_u32 v130, v6, 11, v5
	v_bfe_i32 v5, v0, 27, 1
	v_lshrrev_b32_e32 v5, 22, v5
	v_add_u32_e32 v5, v4, v5
	v_and_b32_e32 v5, 0xfffffc00, v5
	v_sub_u32_e32 v4, v4, v5
	v_lshrrev_b32_e32 v5, 4, v4
	v_bitop3_b32 v6, v5, v4, 32 bitop3:0x6c
	v_ashrrev_i32_e32 v5, 31, v0
	v_lshrrev_b32_e32 v5, 26, v5
	v_ashrrev_i32_e32 v4, 31, v6
	v_add_u32_e32 v5, v0, v5
	v_lshrrev_b32_e32 v4, 26, v4
	v_ashrrev_i32_e32 v5, 6, v5
	s_ashr_i32 s5, s4, 6
	s_ashr_i32 s51, s50, 31
	v_add_u32_e32 v7, v6, v4
	v_lshlrev_b32_e32 v8, 3, v5
	s_ashr_i32 s10, s4, 8
	s_lshl_b32 s13, s5, 10
	s_lshl_b64 s[6:7], s[50:51], 23
	v_ashrrev_i32_e32 v4, 6, v7
	v_and_b32_e32 v8, -16, v8
	s_add_u32 s6, s86, s6
	v_add_u32_e32 v8, v4, v8
	s_addc_u32 s7, s87, s7
	v_and_b32_e32 v9, 3, v4
	v_lshrrev_b32_e32 v10, 2, v8
	v_lshlrev_b32_e32 v11, 1, v8
	v_and_b32_e32 v7, 0xc0, v7
	s_add_u32 s15, s6, 0x2f000000
	v_and_or_b32 v9, v8, s2, v9
	v_and_b32_e32 v10, 4, v10
	v_and_b32_e32 v11, 24, v11
	v_sub_u32_e32 v6, v6, v7
	s_addc_u32 s26, s7, 0
	v_or3_b32 v9, v9, v10, v11
	v_lshlrev_b32_e32 v10, 5, v5
	v_ashrrev_i16_sdwa v6, v12, sext(v6) dst_sel:DWORD dst_unused:UNUSED_PAD src0_sel:DWORD src1_sel:BYTE_0
	v_readlane_b32 s2, v254, 31
	v_and_b32_e32 v10, 32, v10
	v_bfe_i32 v6, v6, 0, 16
	v_readlane_b32 s3, v254, 32
	s_add_u32 s8, s15, s2
	v_add_lshl_u32 v7, v10, v6, 1
	s_addc_u32 s9, s26, s3
	s_add_i32 s27, s13, 0
	v_lshl_add_u32 v132, v9, 11, v7
	s_add_i32 m0, s27, 0x10000
	v_readlane_b32 s2, v254, 54
	global_load_lds_dwordx4 v132, s[8:9]
	s_add_i32 m0, s27, 0x12000
	s_add_u32 s6, s8, 0x40000
	global_load_lds_dwordx4 v128, s[8:9]
	s_addc_u32 s7, s9, 0
	s_add_i32 m0, s27, 0x14000
	v_readlane_b32 s3, v254, 55
	global_load_lds_dwordx4 v132, s[6:7]
	s_add_i32 m0, s27, 0x16000
	v_lshl_add_u32 v134, v8, 11, v7
	global_load_lds_dwordx4 v128, s[6:7]
	s_add_u32 s6, s68, s2
	s_addc_u32 s7, s69, s3
	s_add_i32 s28, s27, 0x2000
	s_mov_b32 m0, s27
	s_add_u32 s40, s6, 0x40000
	global_load_lds_dwordx4 v134, s[6:7]
	s_mov_b32 m0, s28
	s_addc_u32 s41, s7, 0
	s_add_i32 s29, s27, 0x4000
	global_load_lds_dwordx4 v130, s[6:7]
	s_mov_b32 m0, s29
	s_add_i32 s38, s27, 0x6000
	global_load_lds_dwordx4 v134, s[40:41]
	s_mov_b32 m0, s38
	v_writelane_b32 v255, s52, 33
	global_load_lds_dwordx4 v130, s[40:41]
	s_cmp_eq_u32 s10, 1
	v_writelane_b32 v255, s53, 34
	s_mov_b32 s76, s50
	s_cselect_b64 s[40:41], -1, 0
	s_cmp_lg_u32 s10, 1
	s_cbranch_scc1 .LBB0_82
	s_barrier

.LBB0_207:
	s_or_b64 exec, exec, s[8:9]
	s_bitcmp1_b32 s14, 3
	v_readlane_b32 s2, v255, 29
	s_cselect_b32 s44, s2, s66
	v_and_b32_e32 v3, 0xff, v0
	v_readlane_b32 s2, v255, 13
	v_readlane_b32 s3, v255, 30
	s_cselect_b32 s45, s3, s67
	v_lshl_add_u32 v1, v3, 2, s2
	v_cmp_lt_i32_e32 vcc, -1, v4
	v_lshl_add_u32 v1, v2, 10, v1
	v_mov_b32_e32 v30, s5
	v_mov_b32_e32 v31, s4
	v_mov_b32_e32 v33, 0x100
	v_cmp_gt_u32_e64 s[100:101], v33, v0
	s_nop 1
	v_cndmask_b32_e64 v30, v30, v31, s[100:101]
	v_max_i32_e32 v30, 0, v30
	v_lshl_or_b32 v30, v30, 8, v3
	v_mov_b32_e32 v31, 0
	v_lshlrev_b64 v[30:31], 6, v[30:31]
	v_lshl_add_u64 v[30:31], s[44:45], 0, v[30:31]
	global_load_dword v32, v[30:31], off
	s_and_saveexec_b64 s[6:7], vcc
	s_cbranch_execz .LBB0_209
	v_lshl_or_b32 v140, v4, 8, v3
	v_lshlrev_b64 v[4:5], 6, v[140:141]
	v_lshl_add_u64 v[16:17], s[44:45], 0, v[4:5]
	flat_load_dwordx4 v[4:7], v[16:17]
	flat_load_dwordx4 v[8:11], v[16:17] offset:32
	flat_load_dwordx4 v[12:15], v[16:17] offset:16
	s_nop 0
	flat_load_dwordx4 v[16:19], v[16:17] offset:48
	s_waitcnt vmcnt(0) lgkmcnt(0)
	v_mov_b32_e32 v20, v4
	v_mov_b32_e32 v21, v8
	v_mov_b32_e32 v8, v5
	v_mov_b32_e32 v4, v6
	v_mov_b32_e32 v5, v10
	v_mov_b32_e32 v10, v7
	v_mov_b32_e32 v6, v12
	v_mov_b32_e32 v7, v16
	v_mov_b32_e32 v16, v13
	v_mov_b32_e32 v12, v14
	v_mov_b32_e32 v13, v18
	v_mov_b32_e32 v18, v15
	v_pk_add_f32 v[8:9], v[20:21], v[8:9]
	v_pk_add_f32 v[4:5], v[4:5], v[10:11]
	v_pk_add_f32 v[6:7], v[6:7], v[16:17]
	v_pk_add_f32 v[10:11], v[12:13], v[18:19]
	v_pk_add_f32 v[4:5], v[8:9], v[4:5]
	v_pk_add_f32 v[6:7], v[6:7], v[10:11]
	s_nop 0
	v_pk_add_f32 v[4:5], v[4:5], v[6:7]
	s_nop 0
	v_add_f32_e32 v4, v4, v5
	v_fmamk_f32 v4, v4, 0x3a800000, v250
	v_rsq_f32_e32 v4, v4
	ds_write_b32 v1, v4

.LBB0_221:
	s_or_b64 exec, exec, s[6:7]
	s_waitcnt vmcnt(0)
	s_mov_b32 s4, -1
	s_waitcnt vmcnt(0) lgkmcnt(0)
	s_barrier
	s_getreg_b32 s5, hwreg(HW_REG_HW_ID, 0, 6)
	s_and_b32 s5, s5, 63
	s_lshl_b32 s5, s5, 2
	s_add_i32 s5, s5, 0
	s_add_i32 s5, s5, 0x20200
	v_mov_b32_e32 v0, s5
	ds_read_b32 v0, v0
	v_mbcnt_lo_u32_b32 v1, s4, 0
	v_mbcnt_hi_u32_b32 v1, s4, v1
	v_readlane_b32 s2, v253, 5
	v_readlane_b32 s3, v253, 6
	s_waitcnt lgkmcnt(0)
	v_readfirstlane_b32 s4, v0
	s_andn2_b64 vcc, exec, s[2:3]
	s_nop 0
	v_lshl_add_u32 v0, s4, 6, v1
	s_nop 0
	v_readfirstlane_b32 s4, v0
	s_cbranch_vccnz .LBB0_305
	v_lshlrev_b32_e32 v4, 4, v0
	v_add_u32_e32 v2, 0x2000, v4
	v_ashrrev_i32_e32 v1, 31, v2
	v_lshrrev_b32_e32 v1, 22, v1
	v_add_u32_e32 v1, v2, v1
	v_ashrrev_i32_e32 v1, 10, v1
	v_mul_i32_i24_e32 v3, 0x400, v1
	v_sub_u32_e32 v2, v2, v3
	v_lshrrev_b32_e32 v3, 4, v2
	v_bitop3_b32 v3, v3, v2, 32 bitop3:0x6c
	v_ashrrev_i32_e32 v2, 31, v3
	v_lshrrev_b32_e32 v2, 26, v2
	v_add_u32_e32 v5, v3, v2
	v_lshlrev_b32_e32 v6, 3, v1
	v_ashrrev_i32_e32 v2, 6, v5
	v_and_b32_e32 v6, -16, v6
	v_add_u32_e32 v6, v2, v6
	v_and_b32_e32 v7, 3, v2
	s_mov_b32 s2, 0x1fffe0
	v_lshrrev_b32_e32 v8, 2, v6
	v_lshlrev_b32_e32 v9, 1, v6
	v_and_b32_e32 v5, 0xc0, v5
	v_and_or_b32 v7, v6, s2, v7
	v_and_b32_e32 v8, 4, v8
	v_and_b32_e32 v9, 24, v9
	v_sub_u32_e32 v3, v3, v5
	v_mov_b32_e32 v12, 1
	v_or3_b32 v7, v7, v8, v9
	v_lshlrev_b32_e32 v8, 5, v1
	v_ashrrev_i16_sdwa v3, v12, sext(v3) dst_sel:DWORD dst_unused:UNUSED_PAD src0_sel:DWORD src1_sel:BYTE_0
	v_and_b32_e32 v8, 32, v8
	v_bfe_i32 v3, v3, 0, 16
	v_add_lshl_u32 v5, v8, v3, 1
	v_lshl_add_u32 v128, v7, 11, v5
	v_lshl_add_u32 v130, v6, 11, v5
	v_bfe_i32 v5, v0, 27, 1
	v_lshrrev_b32_e32 v5, 22, v5
	v_add_u32_e32 v5, v4, v5
	v_and_b32_e32 v5, 0xfffffc00, v5
	v_sub_u32_e32 v4, v4, v5
	v_lshrrev_b32_e32 v5, 4, v4
	v_bitop3_b32 v6, v5, v4, 32 bitop3:0x6c
	v_ashrrev_i32_e32 v5, 31, v0
	v_lshrrev_b32_e32 v5, 26, v5
	v_ashrrev_i32_e32 v4, 31, v6
	v_add_u32_e32 v5, v0, v5
	v_lshrrev_b32_e32 v4, 26, v4
	v_ashrrev_i32_e32 v5, 6, v5
	v_add_u32_e32 v7, v6, v4
	v_lshlrev_b32_e32 v8, 3, v5
	v_ashrrev_i32_e32 v4, 6, v7
	v_and_b32_e32 v8, -16, v8
	s_ashr_i32 s5, s4, 6
	v_add_u32_e32 v8, v4, v8
	v_and_b32_e32 v9, 3, v4
	s_ashr_i32 s10, s4, 8
	s_lshl_b32 s13, s5, 10
	v_and_or_b32 v9, v8, s2, v9
	v_lshrrev_b32_e32 v10, 2, v8
	v_lshlrev_b32_e32 v11, 1, v8
	v_and_b32_e32 v7, 0xc0, v7
	v_readlane_b32 s2, v254, 44
	v_and_b32_e32 v10, 4, v10
	v_and_b32_e32 v11, 24, v11
	v_sub_u32_e32 v6, v6, v7
	v_readlane_b32 s3, v254, 45
	s_add_u32 s6, s81, s2
	v_or3_b32 v9, v9, v10, v11
	v_lshlrev_b32_e32 v10, 5, v5
	v_ashrrev_i16_sdwa v6, v12, sext(v6) dst_sel:DWORD dst_unused:UNUSED_PAD src0_sel:DWORD src1_sel:BYTE_0
	s_addc_u32 s7, s25, s3
	v_readlane_b32 s2, v254, 28
	v_and_b32_e32 v10, 32, v10
	v_bfe_i32 v6, v6, 0, 16
	v_readlane_b32 s3, v254, 29
	s_add_u32 s8, s6, s2
	v_add_lshl_u32 v7, v10, v6, 1
	s_addc_u32 s9, s7, s3
	s_add_i32 s15, s13, 0
	v_lshl_add_u32 v132, v9, 11, v7
	s_add_i32 m0, s15, 0x10000
	v_readlane_b32 s2, v254, 42
	global_load_lds_dwordx4 v132, s[8:9]
	s_add_i32 m0, s15, 0x12000
	s_add_u32 s6, s8, 0x40000
	global_load_lds_dwordx4 v128, s[8:9]
	s_addc_u32 s7, s9, 0
	s_add_i32 m0, s15, 0x14000
	v_readlane_b32 s3, v254, 43
	global_load_lds_dwordx4 v132, s[6:7]
	s_add_i32 m0, s15, 0x16000
	v_lshl_add_u32 v134, v8, 11, v7
	global_load_lds_dwordx4 v128, s[6:7]
	s_add_u32 s6, s68, s2
	s_addc_u32 s7, s69, s3
	s_add_i32 s26, s15, 0x2000
	s_mov_b32 m0, s15
	s_add_u32 s40, s6, 0x40000
	global_load_lds_dwordx4 v134, s[6:7]
	s_mov_b32 m0, s26
	s_addc_u32 s41, s7, 0
	s_add_i32 s27, s15, 0x4000
	global_load_lds_dwordx4 v130, s[6:7]
	s_mov_b32 m0, s27
	s_add_i32 s28, s15, 0x6000
	global_load_lds_dwordx4 v134, s[40:41]
	s_mov_b32 m0, s28
	v_writelane_b32 v255, s52, 33
	global_load_lds_dwordx4 v130, s[40:41]
	s_nop 0
	v_writelane_b32 v255, s53, 34
	v_writelane_b32 v255, s50, 35
	s_cmp_eq_u32 s10, 1
	s_cselect_b64 s[46:47], -1, 0
	v_writelane_b32 v255, s51, 36
	s_cmp_lg_u32 s10, 1
	s_cbranch_scc1 .LBB0_224
	s_barrier

.LBB0_525:
	s_or_b64 exec, exec, s[8:9]
	v_and_b32_e32 v3, 0xff, v0
	v_readlane_b32 s2, v255, 13
	v_cmp_lt_i32_e32 vcc, -1, v4
	s_nop 0
	v_lshl_add_u32 v1, v3, 2, s2
	v_lshl_add_u32 v1, v2, 10, v1
	v_mov_b32_e32 v30, s5
	v_mov_b32_e32 v31, s4
	v_mov_b32_e32 v33, 0x100
	v_cmp_gt_u32_e64 s[100:101], v33, v0
	s_nop 1
	v_cndmask_b32_e64 v30, v30, v31, s[100:101]
	v_max_i32_e32 v30, 0, v30
	v_lshl_or_b32 v30, v30, 8, v3
	v_mov_b32_e32 v31, 0
	v_lshlrev_b64 v[30:31], 6, v[30:31]
	v_lshl_add_u64 v[30:31], s[48:49], 0, v[30:31]
	global_load_dword v32, v[30:31], off
	s_and_saveexec_b64 s[6:7], vcc
	s_cbranch_execz .LBB0_527
	v_lshl_or_b32 v140, v4, 8, v3
	v_lshlrev_b64 v[4:5], 6, v[140:141]
	v_lshl_add_u64 v[16:17], s[48:49], 0, v[4:5]
	flat_load_dwordx4 v[4:7], v[16:17]
	flat_load_dwordx4 v[8:11], v[16:17] offset:32
	flat_load_dwordx4 v[12:15], v[16:17] offset:16
	s_nop 0
	flat_load_dwordx4 v[16:19], v[16:17] offset:48
	s_waitcnt vmcnt(0) lgkmcnt(0)
	v_mov_b32_e32 v20, v4
	v_mov_b32_e32 v21, v8
	v_mov_b32_e32 v8, v5
	v_mov_b32_e32 v4, v6
	v_mov_b32_e32 v5, v10
	v_mov_b32_e32 v10, v7
	v_mov_b32_e32 v6, v12
	v_mov_b32_e32 v7, v16
	v_mov_b32_e32 v16, v13
	v_mov_b32_e32 v12, v14
	v_mov_b32_e32 v13, v18
	v_mov_b32_e32 v18, v15
	v_pk_add_f32 v[8:9], v[20:21], v[8:9]
	v_pk_add_f32 v[4:5], v[4:5], v[10:11]
	v_pk_add_f32 v[6:7], v[6:7], v[16:17]
	v_pk_add_f32 v[10:11], v[12:13], v[18:19]
	v_pk_add_f32 v[4:5], v[8:9], v[4:5]
	v_pk_add_f32 v[6:7], v[6:7], v[10:11]
	s_nop 0
	v_pk_add_f32 v[4:5], v[4:5], v[6:7]
	s_nop 0
	v_add_f32_e32 v4, v4, v5
	v_fmamk_f32 v4, v4, 0x3a800000, v250
	v_rsq_f32_e32 v4, v4
	ds_write_b32 v1, v4

.LBB0_539:
	s_or_b64 exec, exec, s[6:7]
	s_waitcnt vmcnt(0)
	s_mov_b32 s4, -1
	s_waitcnt vmcnt(0) lgkmcnt(0)
	s_barrier
	s_getreg_b32 s5, hwreg(HW_REG_HW_ID, 0, 6)
	s_and_b32 s5, s5, 63
	s_lshl_b32 s5, s5, 2
	s_add_i32 s5, s5, 0
	s_add_i32 s5, s5, 0x20200
	v_mov_b32_e32 v0, s5
	ds_read_b32 v0, v0
	v_mbcnt_lo_u32_b32 v1, s4, 0
	v_mbcnt_hi_u32_b32 v1, s4, v1
	v_readlane_b32 s2, v253, 9
	v_readlane_b32 s3, v253, 10
	s_waitcnt lgkmcnt(0)
	v_readfirstlane_b32 s4, v0
	s_andn2_b64 vcc, exec, s[2:3]
	s_nop 0
	v_lshl_add_u32 v0, s4, 6, v1
	s_nop 0
	v_readfirstlane_b32 s4, v0
	s_cbranch_vccnz .LBB0_607
	v_lshlrev_b32_e32 v4, 4, v0
	v_add_u32_e32 v2, 0x2000, v4
	v_ashrrev_i32_e32 v1, 31, v2
	v_lshrrev_b32_e32 v1, 22, v1
	v_add_u32_e32 v1, v2, v1
	v_ashrrev_i32_e32 v1, 10, v1
	v_mul_i32_i24_e32 v3, 0x400, v1
	v_sub_u32_e32 v2, v2, v3
	v_lshrrev_b32_e32 v3, 4, v2
	v_bitop3_b32 v3, v3, v2, 32 bitop3:0x6c
	v_ashrrev_i32_e32 v2, 31, v3
	v_lshrrev_b32_e32 v2, 26, v2
	v_add_u32_e32 v5, v3, v2
	v_lshlrev_b32_e32 v6, 3, v1
	v_ashrrev_i32_e32 v2, 6, v5
	v_and_b32_e32 v6, -16, v6
	v_add_u32_e32 v6, v2, v6
	v_and_b32_e32 v7, 3, v2
	s_mov_b32 s2, 0x1fffe0
	v_lshrrev_b32_e32 v8, 2, v6
	v_lshlrev_b32_e32 v9, 1, v6
	v_and_b32_e32 v5, 0xc0, v5
	v_and_or_b32 v7, v6, s2, v7
	v_and_b32_e32 v8, 4, v8
	v_and_b32_e32 v9, 24, v9
	v_sub_u32_e32 v3, v3, v5
	v_mov_b32_e32 v12, 1
	v_or3_b32 v7, v7, v8, v9
	v_lshlrev_b32_e32 v8, 5, v1
	v_ashrrev_i16_sdwa v3, v12, sext(v3) dst_sel:DWORD dst_unused:UNUSED_PAD src0_sel:DWORD src1_sel:BYTE_0
	v_and_b32_e32 v8, 32, v8
	v_bfe_i32 v3, v3, 0, 16
	v_add_lshl_u32 v5, v8, v3, 1
	v_lshl_add_u32 v128, v7, 11, v5
	v_lshl_add_u32 v130, v6, 11, v5
	v_bfe_i32 v5, v0, 27, 1
	v_lshrrev_b32_e32 v5, 22, v5
	v_add_u32_e32 v5, v4, v5
	v_and_b32_e32 v5, 0xfffffc00, v5
	v_sub_u32_e32 v4, v4, v5
	v_lshrrev_b32_e32 v5, 4, v4
	v_bitop3_b32 v6, v5, v4, 32 bitop3:0x6c
	v_ashrrev_i32_e32 v5, 31, v0
	v_lshrrev_b32_e32 v5, 26, v5
	v_ashrrev_i32_e32 v4, 31, v6
	v_add_u32_e32 v5, v0, v5
	v_lshrrev_b32_e32 v4, 26, v4
	v_ashrrev_i32_e32 v5, 6, v5
	s_ashr_i32 s5, s4, 6
	s_ashr_i32 s53, s52, 31
	v_add_u32_e32 v7, v6, v4
	v_lshlrev_b32_e32 v8, 3, v5
	s_ashr_i32 s10, s4, 8
	s_lshl_b32 s12, s5, 10
	s_lshl_b64 s[6:7], s[52:53], 22
	v_ashrrev_i32_e32 v4, 6, v7
	v_and_b32_e32 v8, -16, v8
	s_add_u32 s6, s86, s6
	v_add_u32_e32 v8, v4, v8
	s_addc_u32 s7, s87, s7
	v_and_b32_e32 v9, 3, v4
	v_lshrrev_b32_e32 v10, 2, v8
	v_lshlrev_b32_e32 v11, 1, v8
	v_and_b32_e32 v7, 0xc0, v7
	s_add_u32 s13, s6, 0x34000000
	v_and_or_b32 v9, v8, s2, v9
	v_and_b32_e32 v10, 4, v10
	v_and_b32_e32 v11, 24, v11
	v_sub_u32_e32 v6, v6, v7
	s_addc_u32 s15, s7, 0
	v_or3_b32 v9, v9, v10, v11
	v_lshlrev_b32_e32 v10, 5, v5
	v_ashrrev_i16_sdwa v6, v12, sext(v6) dst_sel:DWORD dst_unused:UNUSED_PAD src0_sel:DWORD src1_sel:BYTE_0
	v_readlane_b32 s2, v254, 34
	v_and_b32_e32 v10, 32, v10
	v_bfe_i32 v6, v6, 0, 16
	v_readlane_b32 s3, v254, 35
	s_add_u32 s8, s13, s2
	v_add_lshl_u32 v7, v10, v6, 1
	s_addc_u32 s9, s15, s3
	s_add_i32 s66, s12, 0
	v_lshl_add_u32 v132, v9, 11, v7
	s_add_i32 m0, s66, 0x10000
	v_readlane_b32 s2, v254, 58
	global_load_lds_dwordx4 v132, s[8:9]
	s_add_i32 m0, s66, 0x12000
	s_add_u32 s6, s8, 0x40000
	global_load_lds_dwordx4 v128, s[8:9]
	s_addc_u32 s7, s9, 0
	s_add_i32 m0, s66, 0x14000
	v_readlane_b32 s3, v254, 59
	global_load_lds_dwordx4 v132, s[6:7]
	s_add_i32 m0, s66, 0x16000
	v_lshl_add_u32 v134, v8, 11, v7
	global_load_lds_dwordx4 v128, s[6:7]
	s_add_u32 s6, s68, s2
	s_addc_u32 s7, s69, s3
	s_add_i32 s67, s66, 0x2000
	s_mov_b32 m0, s66
	s_add_u32 s26, s6, 0x40000
	global_load_lds_dwordx4 v134, s[6:7]
	s_mov_b32 m0, s67
	s_addc_u32 s27, s7, 0
	s_add_i32 s74, s66, 0x4000
	global_load_lds_dwordx4 v130, s[6:7]
	s_mov_b32 m0, s74
	s_add_i32 s75, s66, 0x6000
	global_load_lds_dwordx4 v134, s[26:27]
	s_mov_b32 m0, s75
	s_cmp_eq_u32 s10, 1
	global_load_lds_dwordx4 v130, s[26:27]
	v_mov_b32_e32 v248, 0x3e4ccccd
	s_mov_b32 s60, s50
	s_cselect_b64 s[42:43], -1, 0
	s_cmp_lg_u32 s10, 1
	s_cbranch_scc1 .LBB0_542
	s_barrier
